# branch GEMM mid hook: both batches of scale loads issued together (second batch into dead fragment registers), first wait vmcnt(8); on top of v55
# speedup vs baseline: 1.0063x; 1.0048x over previous
;     __device__ __forceinline__ void mid(f32x4 (&acc)[2][2][4][2], const Unit& u, int wr, int wc, int fr_, int fq_) const {
;         int fr = fr_, fq = fq_; asm volatile("" : "+v"(fr), "+v"(fq));
;         const size_t rowb = (size_t)u.pm * BM + wr * 64 + fr; const bf16_t* gp = GM + 256 * u.pn + 64 * wc + 8 * fq;
; #pragma unroll
;         for (int ai = 0; ai < 2; ++ai) { u32x4 gr[4][2];
; #pragma unroll
;             for (int m = 0; m < 4; ++m)
; #pragma unroll
;                 for (int bj = 0; bj < 2; ++bj) gr[m][bj] = *(const u32x4*)(gp + (rowb + ai * HALF + m * 16) * 2048 + 32 * bj);
;             asm volatile("" : "+v"(gr[0][0]), "+v"(gr[0][1]), "+v"(gr[1][0]), "+v"(gr[1][1]), "+v"(gr[2][0]), "+v"(gr[2][1]), "+v"(gr[3][0]), "+v"(gr[3][1]));
; #pragma unroll
;             for (int m = 0; m < 4; ++m)
; #pragma unroll
;                 for (int bj = 0; bj < 2; ++bj) { f32x4 a0, a1; unpack8(gr[m][bj], a0, a1); acc[ai][bj][m][0] *= a0; acc[ai][bj][m][1] *= a1; }
;             asm volatile("" ::: "memory"); }
.LBB0_600:
	s_and_b64 vcc, exec, s[48:49]
	s_cbranch_vccz .LBB0_602
	v_mov_b32_e32 v4, v229
	v_mov_b32_e32 v2, v230
	s_mov_b32 s46, 0x10000
	v_ashrrev_i32_e32 v5, 31, v4
	v_lshlrev_b32_e32 v134, 3, v2
	v_ashrrev_i32_e32 v135, 31, v134
	v_lshl_add_u64 v[4:5], v[4:5], 0, s[6:7]
	v_lshlrev_b64 v[4:5], 12, v[4:5]
	v_lshl_add_u64 v[134:135], v[134:135], 1, s[22:23]
	v_lshl_add_u64 v[4:5], v[134:135], 0, v[4:5]
	v_add_co_u32_e32 v146, vcc, s46, v4
	s_mov_b32 s46, 0x20000
	s_nop 0
	v_addc_co_u32_e32 v147, vcc, 0, v5, vcc
	v_add_co_u32_e32 v154, vcc, s46, v4
	s_mov_b32 s46, 0x30000
	s_nop 0
	v_addc_co_u32_e32 v155, vcc, 0, v5, vcc
	v_add_co_u32_e32 v162, vcc, s46, v4
	global_load_dwordx4 v[134:137], v[4:5], off
	global_load_dwordx4 v[138:141], v[4:5], off offset:64
	v_addc_co_u32_e32 v163, vcc, 0, v5, vcc
	global_load_dwordx4 v[142:145], v[146:147], off
	s_nop 0
	global_load_dwordx4 v[146:149], v[146:147], off offset:64
	s_nop 0
	global_load_dwordx4 v[150:153], v[154:155], off
	s_nop 0
	global_load_dwordx4 v[154:157], v[154:155], off offset:64
	s_nop 0
	global_load_dwordx4 v[158:161], v[162:163], off
	s_nop 0
	global_load_dwordx4 v[162:165], v[162:163], off offset:64
	v_add_co_u32_e32 v170, vcc, s89, v4
	s_nop 1
	v_addc_co_u32_e32 v171, vcc, 0, v5, vcc
	global_load_dwordx4 v[174:177], v[170:171], off
	global_load_dwordx4 v[178:181], v[170:171], off offset:64
	v_add_co_u32_e32 v172, vcc, s34, v4
	s_nop 1
	v_addc_co_u32_e32 v173, vcc, 0, v5, vcc
	global_load_dwordx4 v[182:185], v[172:173], off
	global_load_dwordx4 v[186:189], v[172:173], off offset:64
	v_add_co_u32_e32 v170, vcc, s90, v4
	s_nop 1
	v_addc_co_u32_e32 v171, vcc, 0, v5, vcc
	global_load_dwordx4 v[206:209], v[170:171], off
	global_load_dwordx4 v[210:213], v[170:171], off offset:64
	v_add_co_u32_e32 v172, vcc, s91, v4
	s_nop 1
	v_addc_co_u32_e32 v173, vcc, 0, v5, vcc
	global_load_dwordx4 v[214:217], v[172:173], off
	global_load_dwordx4 v[218:221], v[172:173], off offset:64
	s_waitcnt vmcnt(8)
	s_nop 0
	v_lshlrev_b32_e32 v170, 16, v134
	v_and_b32_e32 v171, 0xffff0000, v134
	v_lshlrev_b32_e32 v134, 16, v135
	v_and_b32_e32 v135, 0xffff0000, v135
	v_pk_mul_f32 v[132:133], v[132:133], v[134:135]
	v_lshlrev_b32_e32 v134, 16, v138
	v_and_b32_e32 v135, 0xffff0000, v138
	v_pk_mul_f32 v[122:123], v[122:123], v[134:135]
	v_lshlrev_b32_e32 v134, 16, v142
	v_and_b32_e32 v135, 0xffff0000, v142
	v_lshlrev_b32_e32 v172, 16, v136
	v_and_b32_e32 v173, 0xffff0000, v136
	v_lshlrev_b32_e32 v136, 16, v137
	v_and_b32_e32 v137, 0xffff0000, v137
	v_pk_mul_f32 v[114:115], v[114:115], v[134:135]
	v_lshlrev_b32_e32 v134, 16, v146
	v_and_b32_e32 v135, 0xffff0000, v146
	v_pk_mul_f32 v[128:129], v[128:129], v[136:137]
	v_lshlrev_b32_e32 v136, 16, v139
	v_and_b32_e32 v137, 0xffff0000, v139
	v_lshlrev_b32_e32 v138, 16, v140
	v_and_b32_e32 v139, 0xffff0000, v140
	v_lshlrev_b32_e32 v140, 16, v141
	v_and_b32_e32 v141, 0xffff0000, v141
	v_pk_mul_f32 v[106:107], v[106:107], v[134:135]
	v_lshlrev_b32_e32 v134, 16, v150
	v_and_b32_e32 v135, 0xffff0000, v150
	v_pk_mul_f32 v[124:125], v[124:125], v[136:137]
	v_pk_mul_f32 v[120:121], v[120:121], v[140:141]
	v_pk_mul_f32 v[118:119], v[118:119], v[138:139]
	v_lshlrev_b32_e32 v136, 16, v143
	v_and_b32_e32 v137, 0xffff0000, v143
	v_lshlrev_b32_e32 v138, 16, v144
	v_and_b32_e32 v139, 0xffff0000, v144
	v_lshlrev_b32_e32 v140, 16, v145
	v_and_b32_e32 v141, 0xffff0000, v145
	v_pk_mul_f32 v[98:99], v[98:99], v[134:135]
	v_lshlrev_b32_e32 v134, 16, v154
	v_and_b32_e32 v135, 0xffff0000, v154
	v_pk_mul_f32 v[116:117], v[116:117], v[136:137]
	v_pk_mul_f32 v[112:113], v[112:113], v[140:141]
	v_pk_mul_f32 v[110:111], v[110:111], v[138:139]
	v_lshlrev_b32_e32 v136, 16, v147
	v_and_b32_e32 v137, 0xffff0000, v147
	v_lshlrev_b32_e32 v138, 16, v148
	v_and_b32_e32 v139, 0xffff0000, v148
	v_lshlrev_b32_e32 v140, 16, v149
	v_and_b32_e32 v141, 0xffff0000, v149
	v_pk_mul_f32 v[90:91], v[90:91], v[134:135]
	v_lshlrev_b32_e32 v134, 16, v158
	v_and_b32_e32 v135, 0xffff0000, v158
	v_pk_mul_f32 v[108:109], v[108:109], v[136:137]
	v_pk_mul_f32 v[104:105], v[104:105], v[140:141]
	v_pk_mul_f32 v[102:103], v[102:103], v[138:139]
	v_lshlrev_b32_e32 v136, 16, v151
	v_and_b32_e32 v137, 0xffff0000, v151
	v_lshlrev_b32_e32 v138, 16, v152
	v_and_b32_e32 v139, 0xffff0000, v152
	v_lshlrev_b32_e32 v140, 16, v153
	v_and_b32_e32 v141, 0xffff0000, v153
	v_pk_mul_f32 v[82:83], v[82:83], v[134:135]
	v_lshlrev_b32_e32 v134, 16, v162
	v_and_b32_e32 v135, 0xffff0000, v162
	v_pk_mul_f32 v[100:101], v[100:101], v[136:137]
	v_pk_mul_f32 v[96:97], v[96:97], v[140:141]
	v_pk_mul_f32 v[94:95], v[94:95], v[138:139]
	v_lshlrev_b32_e32 v136, 16, v155
	v_and_b32_e32 v137, 0xffff0000, v155
	v_lshlrev_b32_e32 v138, 16, v156
	v_and_b32_e32 v139, 0xffff0000, v156
	v_lshlrev_b32_e32 v140, 16, v157
	v_and_b32_e32 v141, 0xffff0000, v157
	v_pk_mul_f32 v[74:75], v[74:75], v[134:135]
	v_pk_mul_f32 v[92:93], v[92:93], v[136:137]
	v_pk_mul_f32 v[88:89], v[88:89], v[140:141]
	v_pk_mul_f32 v[86:87], v[86:87], v[138:139]
	v_lshlrev_b32_e32 v136, 16, v159
	v_and_b32_e32 v137, 0xffff0000, v159
	v_lshlrev_b32_e32 v138, 16, v160
	v_and_b32_e32 v139, 0xffff0000, v160
	v_lshlrev_b32_e32 v140, 16, v161
	v_and_b32_e32 v141, 0xffff0000, v161
	v_pk_mul_f32 v[84:85], v[84:85], v[136:137]
	v_pk_mul_f32 v[80:81], v[80:81], v[140:141]
	v_pk_mul_f32 v[78:79], v[78:79], v[138:139]
	v_lshlrev_b32_e32 v136, 16, v163
	v_and_b32_e32 v137, 0xffff0000, v163
	v_lshlrev_b32_e32 v138, 16, v164
	v_and_b32_e32 v139, 0xffff0000, v164
	v_lshlrev_b32_e32 v140, 16, v165
	v_and_b32_e32 v141, 0xffff0000, v165
	v_pk_mul_f32 v[76:77], v[76:77], v[136:137]
	s_nop 0
	v_pk_mul_f32 v[72:73], v[72:73], v[140:141]
	s_nop 0
	v_pk_mul_f32 v[70:71], v[70:71], v[138:139]
	s_nop 0
	s_nop 0
	s_nop 0
	s_waitcnt vmcnt(0)
;     __device__ __forceinline__ void mid(f32x4 (&acc)[2][2][4][2], const Unit& u, int wr, int wc, int fr_, int fq_) const {
;     ...
; #pragma unroll
;             for (int m = 0; m < 4; ++m)
; #pragma unroll
;                 for (int bj = 0; bj < 2; ++bj) { f32x4 a0, a1; unpack8(gr[m][bj], a0, a1); acc[ai][bj][m][0] *= a0; acc[ai][bj][m][1] *= a1; }
;             asm volatile("" ::: "memory"); }
	s_nop 0
	v_lshlrev_b32_e32 v4, 16, v174
	v_and_b32_e32 v5, 0xffff0000, v174
	v_pk_mul_f32 v[66:67], v[66:67], v[4:5]
	v_lshlrev_b32_e32 v4, 16, v178
	v_and_b32_e32 v5, 0xffff0000, v178
	v_pk_mul_f32 v[58:59], v[58:59], v[4:5]
	v_lshlrev_b32_e32 v4, 16, v182
	v_and_b32_e32 v5, 0xffff0000, v182
	v_pk_mul_f32 v[50:51], v[50:51], v[4:5]
	v_lshlrev_b32_e32 v4, 16, v186
	v_and_b32_e32 v5, 0xffff0000, v186
	v_pk_mul_f32 v[42:43], v[42:43], v[4:5]
	v_lshlrev_b32_e32 v4, 16, v206
	v_and_b32_e32 v5, 0xffff0000, v206
	v_lshlrev_b32_e32 v138, 16, v207
	v_and_b32_e32 v139, 0xffff0000, v207
	v_pk_mul_f32 v[36:37], v[36:37], v[138:139]
	v_pk_mul_f32 v[34:35], v[34:35], v[4:5]
	v_lshlrev_b32_e32 v4, 16, v210
	v_and_b32_e32 v5, 0xffff0000, v210
	v_lshlrev_b32_e32 v134, 16, v211
	v_and_b32_e32 v135, 0xffff0000, v211
	v_lshlrev_b32_e32 v138, 16, v212
	v_and_b32_e32 v139, 0xffff0000, v212
	v_lshlrev_b32_e32 v136, 16, v213
	v_and_b32_e32 v137, 0xffff0000, v213
	v_lshlrev_b32_e32 v162, 16, v175
	v_and_b32_e32 v163, 0xffff0000, v175
	v_lshlrev_b32_e32 v158, 16, v179
	v_and_b32_e32 v159, 0xffff0000, v179
	v_lshlrev_b32_e32 v154, 16, v183
	v_and_b32_e32 v155, 0xffff0000, v183
	v_lshlrev_b32_e32 v146, 16, v187
	v_and_b32_e32 v147, 0xffff0000, v187
	v_pk_mul_f32 v[28:29], v[28:29], v[134:135]
	v_pk_mul_f32 v[26:27], v[26:27], v[4:5]
	v_pk_mul_f32 v[24:25], v[24:25], v[136:137]
	v_pk_mul_f32 v[22:23], v[22:23], v[138:139]
	v_lshlrev_b32_e32 v4, 16, v214
	v_and_b32_e32 v5, 0xffff0000, v214
	v_lshlrev_b32_e32 v134, 16, v215
	v_and_b32_e32 v135, 0xffff0000, v215
	v_lshlrev_b32_e32 v136, 16, v216
	v_and_b32_e32 v137, 0xffff0000, v216
	v_lshlrev_b32_e32 v138, 16, v217
	v_and_b32_e32 v139, 0xffff0000, v217
	v_pk_mul_f32 v[130:131], v[130:131], v[170:171]
	v_lshlrev_b32_e32 v170, 16, v176
	v_and_b32_e32 v171, 0xffff0000, v176
	v_lshlrev_b32_e32 v164, 16, v177
	v_and_b32_e32 v165, 0xffff0000, v177
	v_pk_mul_f32 v[68:69], v[68:69], v[162:163]
	v_lshlrev_b32_e32 v162, 16, v180
	v_and_b32_e32 v163, 0xffff0000, v180
	v_lshlrev_b32_e32 v160, 16, v181
	v_and_b32_e32 v161, 0xffff0000, v181
	v_pk_mul_f32 v[60:61], v[60:61], v[158:159]
	v_lshlrev_b32_e32 v158, 16, v184
	v_and_b32_e32 v159, 0xffff0000, v184
	v_lshlrev_b32_e32 v156, 16, v185
	v_and_b32_e32 v157, 0xffff0000, v185
	v_pk_mul_f32 v[52:53], v[52:53], v[154:155]
	v_lshlrev_b32_e32 v154, 16, v188
	v_and_b32_e32 v155, 0xffff0000, v188
	v_lshlrev_b32_e32 v148, 16, v189
	v_and_b32_e32 v149, 0xffff0000, v189
	v_pk_mul_f32 v[44:45], v[44:45], v[146:147]
	v_lshlrev_b32_e32 v146, 16, v208
	v_and_b32_e32 v147, 0xffff0000, v208
	v_lshlrev_b32_e32 v140, 16, v209
	v_and_b32_e32 v141, 0xffff0000, v209
	v_pk_mul_f32 v[20:21], v[20:21], v[134:135]
	v_pk_mul_f32 v[18:19], v[18:19], v[4:5]
	v_pk_mul_f32 v[16:17], v[16:17], v[138:139]
	v_pk_mul_f32 v[14:15], v[14:15], v[136:137]
	v_lshlrev_b32_e32 v4, 16, v218
	v_and_b32_e32 v5, 0xffff0000, v218
	v_lshlrev_b32_e32 v134, 16, v219
	v_and_b32_e32 v135, 0xffff0000, v219
	v_lshlrev_b32_e32 v136, 16, v220
	v_and_b32_e32 v137, 0xffff0000, v220
	v_lshlrev_b32_e32 v138, 16, v221
	v_and_b32_e32 v139, 0xffff0000, v221
	v_pk_mul_f32 v[126:127], v[126:127], v[172:173]
	v_pk_mul_f32 v[64:65], v[64:65], v[164:165]
	v_pk_mul_f32 v[62:63], v[62:63], v[170:171]
	v_pk_mul_f32 v[56:57], v[56:57], v[160:161]
	v_pk_mul_f32 v[54:55], v[54:55], v[162:163]
	v_pk_mul_f32 v[48:49], v[48:49], v[156:157]
	v_pk_mul_f32 v[46:47], v[46:47], v[158:159]
	v_pk_mul_f32 v[40:41], v[40:41], v[148:149]
	v_pk_mul_f32 v[38:39], v[38:39], v[154:155]
	v_pk_mul_f32 v[32:33], v[32:33], v[140:141]
	v_pk_mul_f32 v[30:31], v[30:31], v[146:147]
	v_pk_mul_f32 v[12:13], v[12:13], v[134:135]
	v_pk_mul_f32 v[10:11], v[10:11], v[4:5]
	v_pk_mul_f32 v[8:9], v[8:9], v[138:139]
	v_pk_mul_f32 v[6:7], v[6:7], v[136:137]
